# v40 + W_out phase round order transposed (MIXED streamed once)
# baseline (speedup 1.0000x reference)
.LBB0_1112:
	s_ashr_i32 s0, s3, 3
	s_add_i32 s0, s13, s0
	s_ashr_i32 s1, s0, 31
	s_lshr_b32 s1, s1, 26
	s_add_i32 s1, s0, s1
	s_ashr_i32 s3, s1, 6
	s_and_b32 s1, s1, 0xffc0
	s_sub_i32 s0, s0, s1
	s_bfe_i32 s1, s0, 0x80000
	s_bfe_u32 s1, s1, 0x3000c
	s_add_i32 s1, s0, s1
	s_bfe_i32 s10, s1, 0x80000
	s_and_b32 s1, s1, 0xf8
	s_sub_i32 s0, s0, s1
	s_lshl_b32 s3, s3, 3
	s_sext_i32_i16 s10, s10
	s_sext_i32_i8 s0, s0
	s_add_i32 s26, s3, s0
	s_ashr_i32 s24, s10, 3
	s_add_i32 s26, s3, s24
	s_mov_b32 s24, s0

.LBB0_1124:
	s_ashr_i32 s0, s18, 3
	s_add_i32 s0, s20, s0
	s_ashr_i32 s1, s0, 31
	s_lshr_b32 s1, s1, 26
	s_add_i32 s1, s0, s1
	s_ashr_i32 s16, s1, 6
	s_lshl_b32 s17, s16, 3
	s_sub_i32 s16, 64, s17
	s_min_i32 s18, s16, 8
	s_abs_i32 s16, s18
	v_cvt_f32_u32_e32 v2, s16
	s_sub_i32 s20, 0, s16
	s_andn2_b32 s1, s1, 63
	s_sub_i32 s0, s0, s1
	v_rcp_iflag_f32_e32 v2, v2
	s_abs_i32 s1, s0
	s_xor_b32 s19, s0, s18
	s_ashr_i32 s19, s19, 31
	v_mul_f32_e32 v2, 0x4f7ffffe, v2
	v_cvt_u32_f32_e32 v2, v2
	s_nop 0
	v_readfirstlane_b32 s21, v2
	s_mul_i32 s20, s20, s21
	s_mul_hi_u32 s20, s21, s20
	s_add_i32 s21, s21, s20
	s_mul_hi_u32 s20, s1, s21
	s_mul_i32 s21, s20, s16
	s_sub_i32 s1, s1, s21
	s_add_i32 s22, s20, 1
	s_sub_i32 s21, s1, s16
	s_cmp_ge_u32 s1, s16
	s_cselect_b32 s20, s22, s20
	s_cselect_b32 s1, s21, s1
	s_add_i32 s21, s20, 1
	s_cmp_ge_u32 s1, s16
	s_cselect_b32 s1, s21, s20
	s_xor_b32 s1, s1, s19
	s_sub_i32 s16, s1, s19
	s_mul_i32 s1, s16, s18
	s_sub_i32 s0, s0, s1
	s_add_i32 s18, s17, s0
	s_add_i32 s18, s17, s16
	s_mov_b32 s16, s0
